# MLA loop: one static s_setprio 1 for the wave half whose queue-wait flag is clear (PRIOHI), set before the tile loop and cleared at exit
# speedup vs baseline: 1.0109x; 1.0028x over previous
; #define MFMA32(a, b, c) __builtin_amdgcn_mfma_f32_32x32x16_bf16((a), (b), (c), 0, 0, 0)
; #define PG8_LAS __attribute__((address_space(3)))
;     DI float* b1(int l, int v) const { return (float*)(ws + WS_B1) + (l * 2 + v) * 128; }
;     DI float* h() const { return (float*)(__attribute__((address_space(1))) float*)kp->out; }
; template <bool MLA> DI void tile_gload(TileRegs& R, const bf16_t* kp, size_t kst, const bf16_t* vp, size_t vst, const bf16_t* k2p, int kb, int tid) {
;     const int key = tid >> 3, c = tid & 7;
;     R.k = *(const u32x4*)(kp + (size_t)(kb + key) * kst + 8 * c);
;     R.v = *(const u32x4*)(vp + (size_t)(kb + (tid & 63)) * vst + 8 * (tid >> 6));
;     if (MLA) R.k2 = *(const u32x4*)(k2p + (size_t)(kb + ((tid & 255) >> 2)) * 32 + 8 * (tid & 3));
; }
; template <bool MLA> DI void tile_lstore(const TileRegs& R, lbf Ks, lbf Vt, int tid) {
;     constexpr int KLD = MLA ? 104 : 72;
;     const int key = tid >> 3, c = tid & 7;
;     *(PG8_LAS u32x4*)(Ks + key * KLD + 8 * c) = R.k;
;     if (MLA) { if (tid < 256) *(PG8_LAS u32x4*)(Ks + (tid >> 2) * KLD + 64 + 8 * (tid & 3)) = R.k2; }
; template <int KS> DI void qk_tile(lbf Ks, const bf16x8 (&Q)[KS], f32x16& s0, f32x16& s1, int r, int h) {
;     constexpr int KLD = KS == 6 ? 104 : 72;
; #pragma unroll
;     for (int i = 0; i < 16; ++i) { s0[i] = 0.f; s1[i] = 0.f; }
;     const PG8_LAS bf16x8* p0 = (const PG8_LAS bf16x8*)(Ks + r * KLD + 8 * h); const PG8_LAS bf16x8* p1 = (const PG8_LAS bf16x8*)(Ks + (32 + r) * KLD + 8 * h);
;     bf16x8 a0 = p0[0], a1 = p1[0], b0, b1;
; #pragma unroll
;     for (int ks = 0; ks < KS; ks += 2) {
;         b0 = p0[2 * (ks + 1)]; b1 = p1[2 * (ks + 1)];
;         __builtin_amdgcn_sched_barrier(0);
;         s0 = MFMA32(a0, Q[ks], s0); s1 = MFMA32(a1, Q[ks], s1);
;         __builtin_amdgcn_sched_barrier(0);
;         if (ks + 2 < KS) { a0 = p0[2 * (ks + 2)]; a1 = p1[2 * (ks + 2)]; }
;         __builtin_amdgcn_sched_barrier(0);
;         s0 = MFMA32(b0, Q[ks + 1], s0); s1 = MFMA32(b1, Q[ks + 1], s1);
;         __builtin_amdgcn_sched_barrier(0);
;     }
; }
.Lmla_entry:
	v_add_u32_e32 v129, v129, v0
	v_add_u32_e32 v130, v130, v120
	s_mov_b32 s24, 0xd000
	v_add3_u32 v131, v131, v132, s24
	v_add_u32_e32 v136, 0xd000, v136
	v_lshrrev_b32_e32 v170, 3, v214
	v_and_b32_e32 v176, 7, v214
	v_lshlrev_b32_e32 v176, 4, v176
	v_lshl_add_u32 v118, v170, 11, v176
	v_and_b32_e32 v170, 63, v214
	v_lshrrev_b32_e32 v176, 6, v214
	v_lshlrev_b32_e32 v176, 4, v176
	v_lshl_add_u32 v119, v170, 11, v176
	v_bfe_u32 v170, v214, 2, 6
	v_and_b32_e32 v176, 3, v214
	v_lshlrev_b32_e32 v176, 4, v176
	v_lshl_add_u32 v120, v170, 6, v176
	v_readfirstlane_b32 s10, v122
	v_readfirstlane_b32 s11, v123
	v_readfirstlane_b32 s48, v126
	v_readfirstlane_b32 s49, v127
	s_nop 3
	s_add_u32 s10, s10, 0x40000
	s_addc_u32 s11, s11, 0
	s_add_u32 s48, s48, 0x2000
	s_addc_u32 s49, s49, 0
	global_load_dwordx4 v[106:109], v118, s[10:11]
	global_load_dwordx4 v[102:105], v119, s[10:11] offset:1024
	global_load_dwordx4 v[110:113], v120, s[48:49]
	s_lshr_b32 s16, s22, 6
	s_add_i32 s16, s16, 1
	v_readfirstlane_b32 s22, v128
	s_mov_b32 s17, 0
	s_cmp_lg_u64 s[46:47], 0
	s_cselect_b32 s23, 1, 0
	s_lshr_b32 s22, s22, 6
	s_cmp_eq_u32 s23, 0
	s_cbranch_scc0 .Lmla_noprio
	s_setprio 1
.Lmla_noprio:
	ds_read_b128 v[186:189], v135 offset:0
	ds_read_b128 v[190:193], v135 offset:6656
	ds_read_b128 v[194:197], v135 offset:32
	ds_read_b128 v[202:205], v135 offset:6688
	ds_read_b128 v[210:213], v135 offset:64
	ds_read_b128 v[234:237], v135 offset:6720
	s_waitcnt lgkmcnt(5)
	v_mfma_f32_32x32x16_bf16 v[34:49], v[186:189], v[66:69], 0
	s_waitcnt lgkmcnt(4)
	v_mfma_f32_32x32x16_bf16 v[50:65], v[190:193], v[66:69], 0
	ds_read_b128 v[238:241], v135 offset:96
	ds_read_b128 v[242:245], v135 offset:6752
	s_waitcnt lgkmcnt(5)
	v_mfma_f32_32x32x16_bf16 v[34:49], v[194:197], v[70:73], v[34:49]
	s_waitcnt lgkmcnt(4)
	v_mfma_f32_32x32x16_bf16 v[50:65], v[202:205], v[70:73], v[50:65]
	ds_read_b128 v[186:189], v135 offset:128
	ds_read_b128 v[190:193], v135 offset:6784
	s_waitcnt lgkmcnt(5)
	v_mfma_f32_32x32x16_bf16 v[34:49], v[210:213], v[74:77], v[34:49]
	s_waitcnt lgkmcnt(4)
	v_mfma_f32_32x32x16_bf16 v[50:65], v[234:237], v[74:77], v[50:65]
	ds_read_b128 v[194:197], v135 offset:160
	ds_read_b128 v[202:205], v135 offset:6816
	s_waitcnt lgkmcnt(5)
	v_mfma_f32_32x32x16_bf16 v[34:49], v[238:241], v[78:81], v[34:49]
	s_waitcnt lgkmcnt(4)
	v_mfma_f32_32x32x16_bf16 v[50:65], v[242:245], v[78:81], v[50:65]
	s_waitcnt lgkmcnt(3)
	v_mfma_f32_32x32x16_bf16 v[34:49], v[186:189], v[94:97], v[34:49]
	s_waitcnt lgkmcnt(2)
	v_mfma_f32_32x32x16_bf16 v[50:65], v[190:193], v[94:97], v[50:65]
	s_waitcnt lgkmcnt(1)
	v_mfma_f32_32x32x16_bf16 v[34:49], v[194:197], v[98:101], v[34:49]
	s_waitcnt lgkmcnt(0)
	v_mfma_f32_32x32x16_bf16 v[50:65], v[202:205], v[98:101], v[50:65]
	s_waitcnt vmcnt(3)
	ds_write_b128 v129, v[86:89] offset:13312
	s_cmp_eq_u32 s23, 0
	s_cbranch_scc1 .Lmla_p_nor
	ds_write_b128 v130, v[90:93] offset:13440

;     DI bf16_t* kv() const { return (bf16_t*)(ws + WS_KV); }
;     DI bf16_t* mix() const { return (bf16_t*)(ws + WS_MIX); }
;     DI bf16_t* kr() const { return (bf16_t*)(ws + WS_KR); }
;     DI float* h() const { return (float*)(__attribute__((address_space(1))) float*)kp->out; }
; DI void online_raw(f32x16& s0, f32x16& s1, float c1, float& m, float& l, f32x16 (&O)[2]) {
;     ...
;     ls += __shfl_xor(ls, 32);
;     l += ls;
; DI void unit_mla(Frame& F, int b, int hd, int qb, int tid) {
;     ...
;     f32x16 O[2]; zero_o(O); float m = -1e30f, l = 0.f;
;     CfMla cf{Q, O, m, l, t, tq0, r, h};
;     const bf16_t* kvb = F.kv() + (size_t)b * S * 1024;
;     att_pipe<true>(KB, VB, kvb + hd * 64, 1024, kvb + 512 + hd * 64, 1024, F.kr() + (size_t)b * S * 32, TlRange{0, 4 * qb + 3}, cf, tid);
;     write_o(F.mix() + row * DM + hd * 64, O, 1.f / l, h);
.Lmla_exit:
	s_setprio 0
	s_waitcnt vmcnt(0)
	s_nop 7
	v_mov_b32_e32 v170, v134
	s_nop 1
	v_permlane32_swap_b32_e32 v170, v134
	v_add_f32_e32 v134, v134, v170
